# the mid-layer invalidate placed after P2 instead of after P3 (P3's GDN raw-row loads bypass L1)
# speedup vs baseline: 1.0013x; 1.0013x over previous
.LBB0_790:
	s_or_b64 exec, exec, s[18:19]
	s_movk_i32 s6, 0x660
	v_cmp_gt_i32_e32 vcc, s6, v2
	s_and_saveexec_b64 s[18:19], vcc
	s_cbranch_execz .LBB0_792
	s_add_i32 m0, s62, 0x1fc00
	s_nop 0
	global_load_lds_dwordx4 v[0:1], off sc1

.LBB0_794:
	s_or_b64 exec, exec, s[18:19]
	s_movk_i32 s6, 0x460
	v_cmp_gt_i32_e32 vcc, s6, v2
	s_and_saveexec_b64 s[18:19], vcc
	s_cbranch_execz .LBB0_796
	v_readlane_b32 s6, v252, 16
	s_mov_b32 m0, s6
	s_nop 0
	global_load_lds_dwordx4 v[0:1], off sc1

.LBB0_798:
	s_or_b64 exec, exec, s[18:19]
	s_movk_i32 s6, 0x260
	v_cmp_gt_i32_e32 vcc, s6, v2
	s_and_saveexec_b64 s[18:19], vcc
	s_cbranch_execz .LBB0_800
	v_readlane_b32 s6, v252, 17
	s_mov_b32 m0, s6
	s_nop 0
	global_load_lds_dwordx4 v[0:1], off sc1

.LBB0_802:
	s_or_b64 exec, exec, s[14:15]
	s_movk_i32 s6, 0x60
	v_cmp_gt_i32_e32 vcc, s6, v2
	s_and_saveexec_b64 s[12:13], vcc
	s_cbranch_execz .LBB0_804
	v_readlane_b32 s6, v252, 18
	s_mov_b32 m0, s6
	s_nop 0
	global_load_lds_dwordx4 v[0:1], off sc1

.LBB0_820:
	s_or_b64 exec, exec, s[14:15]
	s_movk_i32 s14, 0x660
	v_cmp_gt_i32_e32 vcc, s14, v2
	s_and_saveexec_b64 s[14:15], vcc
	s_cbranch_execz .LBB0_822
	s_add_i32 m0, s62, 0x1fc00
	s_nop 0
	global_load_lds_dwordx4 v[0:1], off sc1

.LBB0_824:
	s_or_b64 exec, exec, s[14:15]
	s_movk_i32 s14, 0x460
	v_cmp_gt_i32_e32 vcc, s14, v2
	s_and_saveexec_b64 s[14:15], vcc
	s_cbranch_execz .LBB0_826
	v_readlane_b32 s39, v252, 16
	s_mov_b32 m0, s39
	s_nop 0
	global_load_lds_dwordx4 v[0:1], off sc1

.LBB0_828:
	s_or_b64 exec, exec, s[14:15]
	s_movk_i32 s14, 0x260
	v_cmp_gt_i32_e32 vcc, s14, v2
	s_and_saveexec_b64 s[14:15], vcc
	s_cbranch_execz .LBB0_830
	v_readlane_b32 s39, v252, 17
	s_mov_b32 m0, s39
	s_nop 0
	global_load_lds_dwordx4 v[0:1], off sc1

.LBB0_832:
	s_or_b64 exec, exec, s[14:15]
	s_movk_i32 s14, 0x60
	v_cmp_gt_i32_e32 vcc, s14, v2
	s_and_saveexec_b64 s[14:15], vcc
	s_cbranch_execz .LBB0_834
	v_readlane_b32 s29, v252, 18
	s_mov_b32 m0, s29
	s_nop 0
	global_load_lds_dwordx4 v[0:1], off sc1
